# stack12: attention serial chain between QK and exp/PV shortened (no self-max canonicalisation, no branch-to-branch hop on the common path) on top of stack11
# speedup vs baseline: 1.0071x; 1.0006x over previous
; #define LDS_WAIT() asm volatile("s_waitcnt lgkmcnt(0)" ::: "memory")
; DI float half_max(float x) { const auto rr = __builtin_amdgcn_permlane32_swap(__float_as_uint(x), __float_as_uint(x), false, false); return fmaxf(__uint_as_float(rr[0]), __uint_as_float(rr[1])); }
; DI int crow(int r, int h) { return (r & 3) + 8 * (r >> 2) + 4 * h; }
; DI void attn_unit(const bf16_t* Qb, const bf16_t* Kb, const bf16_t* Vt, bf16_t* MIX, int b, int h, int qb, char* lds, int tid_in) {
;     ...
;             float mx = p[0][0];
; #pragma unroll
;             for (int kb = 0; kb < 4; ++kb)
; #pragma unroll
;                 for (int i = 0; i < 16; ++i) mx = fmaxf(mx, p[kb][i]);
;             mx = half_max(mx);
;             if (t == 0 || __any(mx > 8.f)) {
;                 const float dl = (t == 0) ? mx : fmaxf(mx, 0.f);
;                 m_run += dl;
; #pragma unroll
;                 for (int kb = 0; kb < 4; ++kb)
; #pragma unroll
;                     for (int i = 0; i < 16; ++i) p[kb][i] -= dl;
;                 if (t != 0) {
;                     const float sc = __builtin_amdgcn_exp2f(-dl); l_run *= sc;
;                     if (hh == 0) wsf[r] = sc;
;                     LDS_WAIT();
; #pragma unroll
;                     for (int i = 0; i < 16; ++i) { const float f = wsf[crow(i, hh)]; o0[i] *= f; o1[i] *= f; }
;                 }
.LBB0_457:
	s_or_b64 exec, exec, s[56:57]
	v_max3_f32 v190, v82, v83, v84
	v_max3_f32 v191, v66, v67, v68
	v_max3_f32 v192, v50, v51, v52
	v_max3_f32 v190, v190, v85, v86
	v_max3_f32 v191, v191, v69, v70
	v_max3_f32 v192, v192, v53, v54
	v_max3_f32 v190, v190, v87, v88
	v_max3_f32 v191, v191, v71, v72
	v_max3_f32 v192, v192, v55, v56
	v_max3_f32 v193, v34, v35, v36
	v_max3_f32 v190, v190, v89, v90
	v_max3_f32 v191, v191, v73, v74
	v_max3_f32 v192, v192, v57, v58
	v_max3_f32 v193, v193, v37, v38
	v_max3_f32 v190, v190, v91, v92
	v_max3_f32 v191, v191, v75, v76
	v_max3_f32 v192, v192, v59, v60
	v_max3_f32 v193, v193, v39, v40
	v_max3_f32 v190, v190, v93, v94
	v_max3_f32 v191, v191, v77, v78
	v_max3_f32 v192, v192, v61, v62
	v_max3_f32 v193, v193, v41, v42
	v_max3_f32 v190, v190, v95, v96
	v_max3_f32 v191, v191, v79, v80
	v_max3_f32 v192, v192, v63, v64
	v_max3_f32 v193, v193, v43, v44
	v_max3_f32 v193, v193, v45, v46
	v_max3_f32 v193, v193, v47, v48
	v_max3_f32 v190, v190, v191, v97
	v_max3_f32 v192, v192, v193, v81
	v_max3_f32 v190, v190, v192, v65
	v_max_f32_e32 v190, v190, v49
	v_mov_b32_e32 v191, v190
	s_nop 1
	v_permlane32_swap_b32_e32 v190, v191
	s_cmp_lg_u32 s74, 0
	s_cselect_b64 s[56:57], -1, 0
	s_cmp_eq_u32 s74, 0
	v_max_f32_e32 v190, v190, v191
	s_cbranch_scc1 .LBB0_460
	s_mov_b32 s2, 0x41000000
	v_cmp_lt_f32_e32 vcc, s2, v190
	s_cbranch_vccz .LBB0_467
	v_max_f32_e32 v190, 0, v190
.LBB0_460:
	s_cbranch_execnz .LBB0_462
	s_branch .LBB0_467
.LBB0_462:
	s_andn2_b64 vcc, exec, s[56:57]
	s_cbranch_vccnz .LBB0_466
	v_exp_f32_e64 v191, -v190
	s_and_saveexec_b64 s[56:57], s[38:39]
	ds_write_b32 v151, v191
	s_or_b64 exec, exec, s[56:57]
	s_waitcnt lgkmcnt(0)
	ds_read_b128 v[192:195], v149
	ds_read_b128 v[196:199], v149 offset:32
	ds_read_b128 v[212:215], v149 offset:64
	ds_read_b128 v[216:219], v149 offset:96
	v_mul_f32_e32 v0, v0, v191
	s_waitcnt lgkmcnt(3)
	v_pk_mul_f32 v[20:21], v[20:21], v[194:195]
	s_waitcnt lgkmcnt(2)
	v_pk_mul_f32 v[24:25], v[24:25], v[198:199]
	s_waitcnt lgkmcnt(1)
	v_pk_mul_f32 v[28:29], v[28:29], v[214:215]
	s_waitcnt lgkmcnt(0)
	v_pk_mul_f32 v[32:33], v[32:33], v[218:219]
	v_pk_mul_f32 v[30:31], v[30:31], v[216:217]
	v_pk_mul_f32 v[26:27], v[26:27], v[212:213]
	v_pk_mul_f32 v[22:23], v[22:23], v[196:197]
	v_pk_mul_f32 v[18:19], v[18:19], v[192:193]
	v_pk_mul_f32 v[16:17], v[16:17], v[218:219]
	v_pk_mul_f32 v[12:13], v[12:13], v[214:215]
	v_pk_mul_f32 v[8:9], v[8:9], v[198:199]
	v_pk_mul_f32 v[4:5], v[4:5], v[194:195]
	v_pk_mul_f32 v[14:15], v[14:15], v[216:217]
	v_pk_mul_f32 v[10:11], v[10:11], v[212:213]
	v_pk_mul_f32 v[6:7], v[6:7], v[196:197]
	v_pk_mul_f32 v[2:3], v[2:3], v[192:193]
